# phase 1 modulate: the second half's 16 row loads issued right behind the first half's (free registers), consumed behind counted waits after the first half's stores
# baseline (speedup 1.0000x reference)
.LBB0_139:
	s_add_i32 s6, s33, s41
	v_add_u32_e32 v8, s33, v10
	s_lshr_b32 s6, s6, 12
	v_ashrrev_i32_e32 v9, 31, v8
	v_cmp_gt_i32_e32 vcc, s42, v8
	v_add_u32_e32 v17, 0xffffe000, v8
	v_add_u32_e32 v16, 4, v8
	v_add_u32_e32 v52, 0xffffe004, v8
	v_add_u32_e32 v18, 8, v8
	v_add_u32_e32 v20, 12, v8
	v_add_u32_e32 v22, 16, v8
	v_add_u32_e32 v24, 20, v8
	v_add_u32_e32 v26, 24, v8
	v_add_u32_e32 v28, 28, v8
	v_add_u32_e32 v30, 32, v8
	v_add_u32_e32 v32, 36, v8
	v_add_u32_e32 v34, 40, v8
	s_add_i32 s44, s6, 1
	v_cndmask_b32_e32 v47, 0, v9, vcc
	v_cndmask_b32_e32 v46, v17, v8, vcc
	v_cndmask_b32_e32 v49, v12, v13, vcc
	v_cndmask_b32_e32 v48, v14, v15, vcc
	v_ashrrev_i32_e32 v17, 31, v16
	v_cmp_gt_i32_e32 vcc, s43, v8
	v_add_u32_e32 v54, 0xffffe008, v8
	v_add_u32_e32 v58, 0xffffe00c, v8
	v_add_u32_e32 v62, 0xffffe010, v8
	v_add_u32_e32 v66, 0xffffe014, v8
	v_add_u32_e32 v70, 0xffffe018, v8
	v_add_u32_e32 v74, 0xffffe01c, v8
	v_add_u32_e32 v78, 0xffffe020, v8
	v_add_u32_e32 v80, 0xffffe024, v8
	v_add_u32_e32 v84, 0xffffe028, v8
	v_add_u32_e32 v36, 44, v8
	v_add_u32_e32 v88, 0xffffe02c, v8
	v_add_u32_e32 v38, 48, v8
	v_add_u32_e32 v92, 0xffffe030, v8
	v_add_u32_e32 v40, 52, v8
	v_add_u32_e32 v98, 0xffffe034, v8
	v_add_u32_e32 v42, 56, v8
	v_add_u32_e32 v102, 0xffffe038, v8
	v_add_u32_e32 v44, 60, v8
	v_add_u32_e32 v106, 0xffffe03c, v8
	v_ashrrev_i32_e32 v19, 31, v18
	v_cmp_gt_i32_e64 s[6:7], s42, v18
	v_ashrrev_i32_e32 v21, 31, v20
	v_cmp_gt_i32_e64 s[8:9], s46, v8
	v_ashrrev_i32_e32 v23, 31, v22
	v_cmp_gt_i32_e64 s[10:11], s42, v22
	v_ashrrev_i32_e32 v25, 31, v24
	v_cmp_gt_i32_e64 s[12:13], s47, v8
	v_ashrrev_i32_e32 v27, 31, v26
	v_cmp_gt_i32_e64 s[14:15], s42, v26
	v_ashrrev_i32_e32 v29, 31, v28
	v_cmp_gt_i32_e64 s[16:17], s48, v8
	v_lshlrev_b64 v[50:51], 11, v[8:9]
	v_ashrrev_i32_e32 v31, 31, v30
	v_cmp_gt_i32_e64 s[18:19], s42, v30
	v_ashrrev_i32_e32 v33, 31, v32
	v_cmp_gt_i32_e64 s[20:21], s56, v8
	v_ashrrev_i32_e32 v35, 31, v34
	v_cmp_gt_i32_e64 s[22:23], s42, v34
	v_cmp_gt_i32_e64 s[24:25], s57, v8
	v_cmp_gt_i32_e64 s[28:29], s58, v8
	s_cmpk_gt_i32 s59, 0x7f
	v_lshlrev_b64 v[8:9], 12, v[46:47]
	v_cndmask_b32_e32 v47, 0, v17, vcc
	v_cndmask_b32_e32 v46, v52, v16, vcc
	v_ashrrev_i32_e32 v37, 31, v36
	v_ashrrev_i32_e32 v39, 31, v38
	v_cmp_gt_i32_e64 s[26:27], s42, v38
	v_ashrrev_i32_e32 v41, 31, v40
	v_ashrrev_i32_e32 v43, 31, v42
	v_cmp_gt_i32_e64 s[30:31], s42, v42
	v_ashrrev_i32_e32 v45, 31, v44
	v_cmp_gt_i32_e64 s[34:35], s42, v44
	v_cndmask_b32_e32 v53, v12, v13, vcc
	v_cndmask_b32_e32 v52, v14, v15, vcc
	v_cndmask_b32_e64 v55, 0, v19, s[6:7]
	v_cndmask_b32_e64 v54, v54, v18, s[6:7]
	v_cndmask_b32_e64 v57, v12, v13, s[6:7]
	v_cndmask_b32_e64 v56, v14, v15, s[6:7]
	v_cndmask_b32_e64 v59, 0, v21, s[8:9]
	v_cndmask_b32_e64 v58, v58, v20, s[8:9]
	v_cndmask_b32_e64 v63, 0, v23, s[10:11]
	v_cndmask_b32_e64 v62, v62, v22, s[10:11]
	v_cndmask_b32_e64 v67, 0, v25, s[12:13]
	v_cndmask_b32_e64 v66, v66, v24, s[12:13]
	v_cndmask_b32_e64 v71, 0, v27, s[14:15]
	v_cndmask_b32_e64 v70, v70, v26, s[14:15]
	v_cndmask_b32_e64 v75, 0, v29, s[16:17]
	v_cndmask_b32_e64 v74, v74, v28, s[16:17]
	v_lshl_add_u64 v[96:97], v[4:5], 0, v[50:51]
	v_lshlrev_b64 v[16:17], 11, v[16:17]
	v_cndmask_b32_e64 v51, 0, v31, s[18:19]
	v_cndmask_b32_e64 v50, v78, v30, s[18:19]
	v_cndmask_b32_e64 v81, 0, v33, s[20:21]
	v_cndmask_b32_e64 v80, v80, v32, s[20:21]
	v_cndmask_b32_e64 v85, 0, v35, s[22:23]
	v_cndmask_b32_e64 v84, v84, v34, s[22:23]
	v_lshlrev_b64 v[30:31], 11, v[30:31]
	v_lshlrev_b64 v[110:111], 11, v[32:33]
	v_lshlrev_b64 v[112:113], 11, v[34:35]
	s_cselect_b32 s6, s44, 0
	v_lshl_add_u64 v[32:33], v[48:49], 0, v[8:9]
	v_lshlrev_b64 v[34:35], 12, v[46:47]
	v_cndmask_b32_e64 v61, v12, v13, s[8:9]
	v_cndmask_b32_e64 v60, v14, v15, s[8:9]
	v_cndmask_b32_e64 v65, v12, v13, s[10:11]
	v_cndmask_b32_e64 v64, v14, v15, s[10:11]
	v_cndmask_b32_e64 v69, v12, v13, s[12:13]
	v_cndmask_b32_e64 v68, v14, v15, s[12:13]
	v_cndmask_b32_e64 v73, v12, v13, s[14:15]
	v_cndmask_b32_e64 v72, v14, v15, s[14:15]
	v_cndmask_b32_e64 v77, v12, v13, s[16:17]
	v_cndmask_b32_e64 v76, v14, v15, s[16:17]
	v_lshlrev_b64 v[18:19], 11, v[18:19]
	v_lshlrev_b64 v[20:21], 11, v[20:21]
	v_lshlrev_b64 v[22:23], 11, v[22:23]
	v_lshlrev_b64 v[24:25], 11, v[24:25]
	v_lshlrev_b64 v[26:27], 11, v[26:27]
	v_lshlrev_b64 v[28:29], 11, v[28:29]
	v_cndmask_b32_e64 v89, 0, v37, s[24:25]
	v_cndmask_b32_e64 v88, v88, v36, s[24:25]
	v_cndmask_b32_e64 v93, 0, v39, s[26:27]
	v_cndmask_b32_e64 v92, v92, v38, s[26:27]
	v_cndmask_b32_e64 v99, 0, v41, s[28:29]
	v_cndmask_b32_e64 v98, v98, v40, s[28:29]
	v_cndmask_b32_e64 v103, 0, v43, s[30:31]
	v_cndmask_b32_e64 v102, v102, v42, s[30:31]
	v_cndmask_b32_e64 v107, 0, v45, s[34:35]
	v_cndmask_b32_e64 v106, v106, v44, s[34:35]
	v_lshlrev_b64 v[114:115], 11, v[36:37]
	v_lshlrev_b64 v[116:117], 11, v[38:39]
	v_lshlrev_b64 v[118:119], 11, v[40:41]
	v_lshlrev_b64 v[120:121], 11, v[42:43]
	v_lshlrev_b64 v[122:123], 11, v[44:45]
	v_lshlrev_b64 v[36:37], 12, v[54:55]
	v_lshlrev_b64 v[38:39], 12, v[58:59]
	v_lshlrev_b64 v[40:41], 12, v[62:63]
	v_lshlrev_b64 v[42:43], 12, v[66:67]
	v_lshlrev_b64 v[44:45], 12, v[70:71]
	v_lshlrev_b64 v[46:47], 12, v[74:75]
	v_lshl_add_u64 v[124:125], v[4:5], 0, v[16:17]
	v_lshlrev_b64 v[16:17], 12, v[50:51]
	v_lshl_add_u64 v[8:9], v[4:5], 0, v[30:31]
	v_mad_u64_u32 v[50:51], s[6:7], s6, v11, v[6:7]
	v_lshl_add_u64 v[30:31], v[32:33], 0, v[2:3]
	v_lshl_add_u64 v[32:33], v[52:53], 0, v[34:35]
	v_cndmask_b32_e64 v79, v12, v13, s[18:19]
	v_cndmask_b32_e64 v78, v14, v15, s[18:19]
	v_cndmask_b32_e64 v83, v12, v13, s[20:21]
	v_cndmask_b32_e64 v82, v14, v15, s[20:21]
	v_cndmask_b32_e64 v87, v12, v13, s[22:23]
	v_cndmask_b32_e64 v86, v14, v15, s[22:23]
	v_cndmask_b32_e64 v91, v12, v13, s[24:25]
	v_cndmask_b32_e64 v90, v14, v15, s[24:25]
	v_cndmask_b32_e64 v95, v12, v13, s[26:27]
	v_cndmask_b32_e64 v94, v14, v15, s[26:27]
	v_cndmask_b32_e64 v101, v12, v13, s[28:29]
	v_cndmask_b32_e64 v100, v14, v15, s[28:29]
	v_cndmask_b32_e64 v105, v12, v13, s[30:31]
	v_cndmask_b32_e64 v104, v14, v15, s[30:31]
	v_cndmask_b32_e64 v109, v12, v13, s[34:35]
	v_cndmask_b32_e64 v108, v14, v15, s[34:35]
	v_lshl_add_u64 v[126:127], v[4:5], 0, v[18:19]
	v_lshl_add_u64 v[128:129], v[4:5], 0, v[20:21]
	v_lshl_add_u64 v[130:131], v[4:5], 0, v[22:23]
	v_lshl_add_u64 v[132:133], v[4:5], 0, v[24:25]
	v_lshl_add_u64 v[134:135], v[4:5], 0, v[26:27]
	v_lshl_add_u64 v[136:137], v[4:5], 0, v[28:29]
	v_lshlrev_b64 v[18:19], 12, v[80:81]
	v_lshlrev_b64 v[20:21], 12, v[84:85]
	v_lshlrev_b64 v[22:23], 12, v[88:89]
	v_lshlrev_b64 v[24:25], 12, v[92:93]
	v_lshlrev_b64 v[26:27], 12, v[98:99]
	v_lshlrev_b64 v[28:29], 12, v[102:103]
	v_lshlrev_b64 v[48:49], 12, v[106:107]
	v_lshl_add_u64 v[34:35], v[56:57], 0, v[36:37]
	v_lshl_add_u64 v[36:37], v[60:61], 0, v[38:39]
	v_lshl_add_u64 v[38:39], v[64:65], 0, v[40:41]
	v_lshl_add_u64 v[40:41], v[68:69], 0, v[42:43]
	v_lshl_add_u64 v[42:43], v[72:73], 0, v[44:45]
	v_lshl_add_u64 v[44:45], v[76:77], 0, v[46:47]
	v_lshl_add_u64 v[66:67], v[32:33], 0, v[2:3]
	v_add_co_u32_e32 v32, vcc, s49, v50
	v_lshl_add_u64 v[46:47], v[78:79], 0, v[16:17]
	v_lshl_add_u64 v[52:53], v[82:83], 0, v[18:19]
	v_lshl_add_u64 v[54:55], v[86:87], 0, v[20:21]
	v_lshl_add_u64 v[56:57], v[90:91], 0, v[22:23]
	v_lshl_add_u64 v[58:59], v[94:95], 0, v[24:25]
	v_lshl_add_u64 v[60:61], v[100:101], 0, v[26:27]
	v_lshl_add_u64 v[62:63], v[104:105], 0, v[28:29]
	v_lshl_add_u64 v[48:49], v[108:109], 0, v[48:49]
	v_lshl_add_u64 v[64:65], v[50:51], 0, s[38:39]
	global_load_dwordx4 v[16:19], v[30:31], off offset:16
	global_load_dwordx4 v[20:23], v[30:31], off
	v_lshl_add_u64 v[68:69], v[34:35], 0, v[2:3]
	v_lshl_add_u64 v[70:71], v[36:37], 0, v[2:3]
	v_lshl_add_u64 v[72:73], v[38:39], 0, v[2:3]
	v_lshl_add_u64 v[76:77], v[40:41], 0, v[2:3]
	v_lshl_add_u64 v[84:85], v[42:43], 0, v[2:3]
	v_lshl_add_u64 v[92:93], v[44:45], 0, v[2:3]
	global_load_dwordx4 v[24:27], v[50:51], off offset:16
	global_load_dwordx4 v[28:31], v[50:51], off
	v_addc_co_u32_e32 v33, vcc, 0, v51, vcc
	v_lshl_add_u64 v[98:99], v[46:47], 0, v[2:3]
	v_lshl_add_u64 v[100:101], v[52:53], 0, v[2:3]
	v_lshl_add_u64 v[102:103], v[54:55], 0, v[2:3]
	v_lshl_add_u64 v[104:105], v[56:57], 0, v[2:3]
	v_lshl_add_u64 v[106:107], v[58:59], 0, v[2:3]
	v_lshl_add_u64 v[108:109], v[60:61], 0, v[2:3]
	v_lshl_add_u64 v[138:139], v[62:63], 0, v[2:3]
	v_lshl_add_u64 v[140:141], v[48:49], 0, v[2:3]
	global_load_dwordx4 v[32:35], v[32:33], off
	s_nop 0
	global_load_dwordx4 v[36:39], v[64:65], off offset:16
	global_load_dwordx4 v[40:43], v[66:67], off
	global_load_dwordx4 v[44:47], v[66:67], off offset:16
	global_load_dwordx4 v[48:51], v[68:69], off
	global_load_dwordx4 v[52:55], v[68:69], off offset:16
	global_load_dwordx4 v[56:59], v[70:71], off
	global_load_dwordx4 v[60:63], v[70:71], off offset:16
	s_nop 0
	global_load_dwordx4 v[64:67], v[72:73], off
	global_load_dwordx4 v[68:71], v[72:73], off offset:16
	s_nop 0
	global_load_dwordx4 v[72:75], v[76:77], off
	s_nop 0
	global_load_dwordx4 v[76:79], v[76:77], off offset:16
	s_nop 0
	global_load_dwordx4 v[80:83], v[84:85], off
	s_nop 0
	global_load_dwordx4 v[84:87], v[84:85], off offset:16
	s_nop 0
	global_load_dwordx4 v[88:91], v[92:93], off
	s_nop 0
	global_load_dwordx4 v[92:95], v[92:93], off offset:16
	global_load_dwordx4 v[150:153], v[98:99], off
	global_load_dwordx4 v[154:157], v[98:99], off offset:16
	global_load_dwordx4 v[158:161], v[100:101], off
	global_load_dwordx4 v[162:165], v[100:101], off offset:16
	global_load_dwordx4 v[166:169], v[102:103], off
	global_load_dwordx4 v[170:173], v[102:103], off offset:16
	global_load_dwordx4 v[192:195], v[104:105], off
	global_load_dwordx4 v[196:199], v[104:105], off offset:16
	global_load_dwordx4 v[200:203], v[106:107], off
	global_load_dwordx4 v[204:207], v[106:107], off offset:16
	global_load_dwordx4 v[208:211], v[108:109], off
	global_load_dwordx4 v[212:215], v[108:109], off offset:16
	global_load_dwordx4 v[216:219], v[138:139], off
	global_load_dwordx4 v[220:223], v[138:139], off offset:16
	global_load_dwordx4 v[224:227], v[140:141], off
	global_load_dwordx4 v[228:231], v[140:141], off offset:16
	s_add_i32 s59, s59, s70
	s_add_i32 s41, s41, s40
	v_add_u32_e32 v10, s40, v10
	s_cmpk_lt_i32 s59, 0x100
	s_waitcnt vmcnt(31)
	v_pk_add_f32 v[142:143], v[32:33], 1.0 op_sel_hi:[1,0]
	v_pk_add_f32 v[144:145], v[34:35], 1.0 op_sel_hi:[1,0]
	s_waitcnt vmcnt(30)
	v_pk_add_f32 v[146:147], v[36:37], 1.0 op_sel_hi:[1,0]
	v_pk_add_f32 v[148:149], v[38:39], 1.0 op_sel_hi:[1,0]
	v_pk_fma_f32 v[20:21], v[142:143], v[20:21], v[28:29]
	v_pk_fma_f32 v[22:23], v[144:145], v[22:23], v[30:31]
	v_pk_fma_f32 v[32:33], v[146:147], v[16:17], v[24:25]
	v_pk_fma_f32 v[34:35], v[148:149], v[18:19], v[26:27]
	s_waitcnt vmcnt(29)
	v_pk_fma_f32 v[36:37], v[142:143], v[40:41], v[28:29]
	v_pk_fma_f32 v[38:39], v[144:145], v[42:43], v[30:31]
	s_waitcnt vmcnt(28)
	v_pk_fma_f32 v[40:41], v[146:147], v[44:45], v[24:25]
	v_pk_fma_f32 v[42:43], v[148:149], v[46:47], v[26:27]
	s_waitcnt vmcnt(27)
	v_pk_fma_f32 v[44:45], v[142:143], v[48:49], v[28:29]
	v_pk_fma_f32 v[46:47], v[144:145], v[50:51], v[30:31]
	s_waitcnt vmcnt(26)
	v_pk_fma_f32 v[48:49], v[146:147], v[52:53], v[24:25]
	v_pk_fma_f32 v[50:51], v[148:149], v[54:55], v[26:27]
	s_waitcnt vmcnt(25)
	v_pk_fma_f32 v[52:53], v[142:143], v[56:57], v[28:29]
	v_pk_fma_f32 v[54:55], v[144:145], v[58:59], v[30:31]
	s_waitcnt vmcnt(24)
	v_pk_fma_f32 v[56:57], v[146:147], v[60:61], v[24:25]
	v_pk_fma_f32 v[58:59], v[148:149], v[62:63], v[26:27]
	s_waitcnt vmcnt(23)
	v_pk_fma_f32 v[60:61], v[142:143], v[64:65], v[28:29]
	v_pk_fma_f32 v[62:63], v[144:145], v[66:67], v[30:31]
	s_waitcnt vmcnt(22)
	v_pk_fma_f32 v[64:65], v[146:147], v[68:69], v[24:25]
	v_pk_fma_f32 v[66:67], v[148:149], v[70:71], v[26:27]
	s_waitcnt vmcnt(21)
	v_pk_fma_f32 v[68:69], v[142:143], v[72:73], v[28:29]
	v_pk_fma_f32 v[70:71], v[144:145], v[74:75], v[30:31]
	s_waitcnt vmcnt(20)
	v_pk_fma_f32 v[72:73], v[146:147], v[76:77], v[24:25]
	v_pk_fma_f32 v[74:75], v[148:149], v[78:79], v[26:27]
	s_waitcnt vmcnt(19)
	v_pk_fma_f32 v[76:77], v[142:143], v[80:81], v[28:29]
	v_pk_fma_f32 v[78:79], v[144:145], v[82:83], v[30:31]
	s_waitcnt vmcnt(18)
	v_pk_fma_f32 v[80:81], v[146:147], v[84:85], v[24:25]
	v_pk_fma_f32 v[82:83], v[148:149], v[86:87], v[26:27]
	s_waitcnt vmcnt(17)
	v_pk_fma_f32 v[84:85], v[142:143], v[88:89], v[28:29]
	v_pk_fma_f32 v[86:87], v[144:145], v[90:91], v[30:31]
	s_waitcnt vmcnt(16)
	v_pk_fma_f32 v[88:89], v[146:147], v[92:93], v[24:25]
	v_pk_fma_f32 v[90:91], v[148:149], v[94:95], v[26:27]
	v_cvt_pk_bf16_f32 v16, v20, v21
	v_cvt_pk_bf16_f32 v17, v22, v23
	v_cvt_pk_bf16_f32 v18, v32, v33
	v_cvt_pk_bf16_f32 v19, v34, v35
	v_cvt_pk_bf16_f32 v20, v36, v37
	v_cvt_pk_bf16_f32 v21, v38, v39
	v_cvt_pk_bf16_f32 v22, v40, v41
	v_cvt_pk_bf16_f32 v23, v42, v43
	v_cvt_pk_bf16_f32 v32, v44, v45
	v_cvt_pk_bf16_f32 v33, v46, v47
	v_cvt_pk_bf16_f32 v34, v48, v49
	v_cvt_pk_bf16_f32 v35, v50, v51
	v_cvt_pk_bf16_f32 v36, v52, v53
	v_cvt_pk_bf16_f32 v37, v54, v55
	v_cvt_pk_bf16_f32 v38, v56, v57
	v_cvt_pk_bf16_f32 v39, v58, v59
	v_cvt_pk_bf16_f32 v40, v60, v61
	v_cvt_pk_bf16_f32 v41, v62, v63
	v_cvt_pk_bf16_f32 v42, v64, v65
	v_cvt_pk_bf16_f32 v43, v66, v67
	v_cvt_pk_bf16_f32 v44, v68, v69
	v_cvt_pk_bf16_f32 v45, v70, v71
	v_cvt_pk_bf16_f32 v46, v72, v73
	v_cvt_pk_bf16_f32 v47, v74, v75
	v_cvt_pk_bf16_f32 v48, v76, v77
	v_cvt_pk_bf16_f32 v49, v78, v79
	v_cvt_pk_bf16_f32 v50, v80, v81
	v_cvt_pk_bf16_f32 v51, v82, v83
	v_cvt_pk_bf16_f32 v52, v84, v85
	v_cvt_pk_bf16_f32 v53, v86, v87
	v_cvt_pk_bf16_f32 v54, v88, v89
	v_cvt_pk_bf16_f32 v55, v90, v91
	global_store_dwordx4 v[96:97], v[16:19], off
	global_store_dwordx4 v[124:125], v[20:23], off
	global_store_dwordx4 v[126:127], v[32:35], off
	global_store_dwordx4 v[128:129], v[36:39], off
	global_store_dwordx4 v[130:131], v[40:43], off
	global_store_dwordx4 v[132:133], v[44:47], off
	global_store_dwordx4 v[134:135], v[48:51], off
	global_store_dwordx4 v[136:137], v[52:55], off
	v_lshl_add_u64 v[88:89], v[4:5], 0, v[110:111]
	v_lshl_add_u64 v[90:91], v[4:5], 0, v[112:113]
	v_lshl_add_u64 v[92:93], v[4:5], 0, v[114:115]
	v_lshl_add_u64 v[94:95], v[4:5], 0, v[116:117]
	v_lshl_add_u64 v[96:97], v[4:5], 0, v[118:119]
	v_lshl_add_u64 v[98:99], v[4:5], 0, v[120:121]
	v_lshl_add_u64 v[100:101], v[4:5], 0, v[122:123]
	s_waitcnt vmcnt(23)
	v_mov_b32_e32 v16, v150
	v_mov_b32_e32 v17, v151
	v_mov_b32_e32 v18, v152
	v_mov_b32_e32 v19, v153
	v_pk_fma_f32 v[16:17], v[142:143], v[16:17], v[28:29]
	v_pk_fma_f32 v[18:19], v[144:145], v[18:19], v[30:31]
	s_waitcnt vmcnt(22)
	v_mov_b32_e32 v20, v154
	v_mov_b32_e32 v21, v155
	v_mov_b32_e32 v22, v156
	v_mov_b32_e32 v23, v157
	v_pk_fma_f32 v[20:21], v[146:147], v[20:21], v[24:25]
	v_pk_fma_f32 v[22:23], v[148:149], v[22:23], v[26:27]
	s_waitcnt vmcnt(21)
	v_mov_b32_e32 v32, v158
	v_mov_b32_e32 v33, v159
	v_mov_b32_e32 v34, v160
	v_mov_b32_e32 v35, v161
	v_pk_fma_f32 v[32:33], v[142:143], v[32:33], v[28:29]
	v_pk_fma_f32 v[34:35], v[144:145], v[34:35], v[30:31]
	s_waitcnt vmcnt(20)
	v_mov_b32_e32 v36, v162
	v_mov_b32_e32 v37, v163
	v_mov_b32_e32 v38, v164
	v_mov_b32_e32 v39, v165
	v_pk_fma_f32 v[36:37], v[146:147], v[36:37], v[24:25]
	v_pk_fma_f32 v[38:39], v[148:149], v[38:39], v[26:27]
	s_waitcnt vmcnt(19)
	v_mov_b32_e32 v40, v166
	v_mov_b32_e32 v41, v167
	v_mov_b32_e32 v42, v168
	v_mov_b32_e32 v43, v169
	v_pk_fma_f32 v[40:41], v[142:143], v[40:41], v[28:29]
	v_pk_fma_f32 v[42:43], v[144:145], v[42:43], v[30:31]
	s_waitcnt vmcnt(18)
	v_mov_b32_e32 v44, v170
	v_mov_b32_e32 v45, v171
	v_mov_b32_e32 v46, v172
	v_mov_b32_e32 v47, v173
	v_pk_fma_f32 v[44:45], v[146:147], v[44:45], v[24:25]
	v_pk_fma_f32 v[46:47], v[148:149], v[46:47], v[26:27]
	s_waitcnt vmcnt(17)
	v_mov_b32_e32 v48, v192
	v_mov_b32_e32 v49, v193
	v_mov_b32_e32 v50, v194
	v_mov_b32_e32 v51, v195
	v_pk_fma_f32 v[48:49], v[142:143], v[48:49], v[28:29]
	v_pk_fma_f32 v[50:51], v[144:145], v[50:51], v[30:31]
	s_waitcnt vmcnt(16)
	v_mov_b32_e32 v52, v196
	v_mov_b32_e32 v53, v197
	v_mov_b32_e32 v54, v198
	v_mov_b32_e32 v55, v199
	v_pk_fma_f32 v[52:53], v[146:147], v[52:53], v[24:25]
	v_pk_fma_f32 v[54:55], v[148:149], v[54:55], v[26:27]
	s_waitcnt vmcnt(15)
	v_mov_b32_e32 v56, v200
	v_mov_b32_e32 v57, v201
	v_mov_b32_e32 v58, v202
	v_mov_b32_e32 v59, v203
	v_pk_fma_f32 v[56:57], v[142:143], v[56:57], v[28:29]
	v_pk_fma_f32 v[58:59], v[144:145], v[58:59], v[30:31]
	s_waitcnt vmcnt(14)
	v_mov_b32_e32 v60, v204
	v_mov_b32_e32 v61, v205
	v_mov_b32_e32 v62, v206
	v_mov_b32_e32 v63, v207
	v_pk_fma_f32 v[60:61], v[146:147], v[60:61], v[24:25]
	v_pk_fma_f32 v[62:63], v[148:149], v[62:63], v[26:27]
	s_waitcnt vmcnt(13)
	v_mov_b32_e32 v64, v208
	v_mov_b32_e32 v65, v209
	v_mov_b32_e32 v66, v210
	v_mov_b32_e32 v67, v211
	v_pk_fma_f32 v[64:65], v[142:143], v[64:65], v[28:29]
	v_pk_fma_f32 v[66:67], v[144:145], v[66:67], v[30:31]
	s_waitcnt vmcnt(12)
	v_mov_b32_e32 v68, v212
	v_mov_b32_e32 v69, v213
	v_mov_b32_e32 v70, v214
	v_mov_b32_e32 v71, v215
	v_pk_fma_f32 v[68:69], v[146:147], v[68:69], v[24:25]
	v_pk_fma_f32 v[70:71], v[148:149], v[70:71], v[26:27]
	s_waitcnt vmcnt(11)
	v_mov_b32_e32 v72, v216
	v_mov_b32_e32 v73, v217
	v_mov_b32_e32 v74, v218
	v_mov_b32_e32 v75, v219
	v_pk_fma_f32 v[72:73], v[142:143], v[72:73], v[28:29]
	v_pk_fma_f32 v[74:75], v[144:145], v[74:75], v[30:31]
	s_waitcnt vmcnt(10)
	v_mov_b32_e32 v76, v220
	v_mov_b32_e32 v77, v221
	v_mov_b32_e32 v78, v222
	v_mov_b32_e32 v79, v223
	v_pk_fma_f32 v[76:77], v[146:147], v[76:77], v[24:25]
	v_pk_fma_f32 v[78:79], v[148:149], v[78:79], v[26:27]
	s_waitcnt vmcnt(9)
	v_mov_b32_e32 v80, v224
	v_mov_b32_e32 v81, v225
	v_mov_b32_e32 v82, v226
	v_mov_b32_e32 v83, v227
	v_pk_fma_f32 v[80:81], v[142:143], v[80:81], v[28:29]
	v_pk_fma_f32 v[82:83], v[144:145], v[82:83], v[30:31]
	s_waitcnt vmcnt(8)
	v_mov_b32_e32 v84, v228
	v_mov_b32_e32 v85, v229
	v_mov_b32_e32 v86, v230
	v_mov_b32_e32 v87, v231
	v_pk_fma_f32 v[84:85], v[146:147], v[84:85], v[24:25]
	v_pk_fma_f32 v[86:87], v[148:149], v[86:87], v[26:27]
	v_cvt_pk_bf16_f32 v16, v16, v17
	v_cvt_pk_bf16_f32 v17, v18, v19
	v_cvt_pk_bf16_f32 v18, v20, v21
	v_cvt_pk_bf16_f32 v19, v22, v23
	v_cvt_pk_bf16_f32 v20, v32, v33
	v_cvt_pk_bf16_f32 v21, v34, v35
	v_cvt_pk_bf16_f32 v22, v36, v37
	v_cvt_pk_bf16_f32 v23, v38, v39
	v_cvt_pk_bf16_f32 v24, v40, v41
	v_cvt_pk_bf16_f32 v25, v42, v43
	v_cvt_pk_bf16_f32 v26, v44, v45
	v_cvt_pk_bf16_f32 v27, v46, v47
	v_cvt_pk_bf16_f32 v28, v48, v49
	v_cvt_pk_bf16_f32 v29, v50, v51
	v_cvt_pk_bf16_f32 v30, v52, v53
	v_cvt_pk_bf16_f32 v31, v54, v55
	v_cvt_pk_bf16_f32 v32, v56, v57
	v_cvt_pk_bf16_f32 v33, v58, v59
	v_cvt_pk_bf16_f32 v34, v60, v61
	v_cvt_pk_bf16_f32 v35, v62, v63
	v_cvt_pk_bf16_f32 v36, v64, v65
	v_cvt_pk_bf16_f32 v37, v66, v67
	v_cvt_pk_bf16_f32 v38, v68, v69
	v_cvt_pk_bf16_f32 v39, v70, v71
	v_cvt_pk_bf16_f32 v40, v72, v73
	v_cvt_pk_bf16_f32 v41, v74, v75
	v_cvt_pk_bf16_f32 v42, v76, v77
	v_cvt_pk_bf16_f32 v43, v78, v79
	v_cvt_pk_bf16_f32 v44, v80, v81
	v_cvt_pk_bf16_f32 v45, v82, v83
	v_cvt_pk_bf16_f32 v46, v84, v85
	v_cvt_pk_bf16_f32 v47, v86, v87
	global_store_dwordx4 v[8:9], v[16:19], off
	global_store_dwordx4 v[88:89], v[20:23], off
	global_store_dwordx4 v[90:91], v[24:27], off
	global_store_dwordx4 v[92:93], v[28:31], off
	global_store_dwordx4 v[94:95], v[32:35], off
	global_store_dwordx4 v[96:97], v[36:39], off
	global_store_dwordx4 v[98:99], v[40:43], off
	global_store_dwordx4 v[100:101], v[44:47], off
	s_cbranch_scc1 .LBB0_139
